# fp6 K-loop rewritten as software-pipelined loop: double-buffered fragments, LDS reads and LDS-DMA issued between MFMAs, one barrier per sub-phase, no half-workgroup stagger
# speedup vs baseline: 1.0317x; 1.0317x over previous
.LBB0_155:
	v_cndmask_b32_e64 v2, 0, 1, s[2:3]
	v_cmp_ne_u32_e64 s[6:7], 1, v2
	s_andn2_b64 vcc, exec, s[2:3]
	s_cbranch_vccnz .LBB0_157
.LBB0_156:
	s_nop 0
.LBB0_157:
	s_waitcnt vmcnt(1)
	s_add_u32 s2, s20, 0x3000
	s_addc_u32 s3, s21, 0
	s_and_b64 vcc, exec, s[0:1]
	s_mov_b64 s[8:9], -1
	s_barrier
	s_cbranch_vccnz .LBB0_159
	s_add_i32 s8, s11, 0
	s_add_i32 m0, s8, 0x18000
	s_nop 0
	global_load_lds_dwordx4 v180, s[2:3]
	s_add_i32 m0, s8, 0x19000
	s_mov_b64 s[8:9], 0
	global_load_lds_dwordx4 v182, s[2:3]

.LBB0_171:
	v_and_b32_e32 v3, 48, v0
	v_lshrrev_b32_e32 v2, 4, v178
	v_lshl_or_b32 v3, v193, 6, v3
	v_lshlrev_b32_e32 v4, 3, v193
	s_lshl_b32 s2, s10, 12
	v_lshl_or_b32 v4, v2, 7, v4
	v_bitop3_b32 v5, s2, v3, v1 bitop3:0xf6
	s_lshl_b32 s2, s12, 11
	v_bitop3_b32 v194, s2, v3, v1 bitop3:0xf6
	v_or_b32_e32 v3, s11, v4
	s_lshl_b32 s2, s12, 5
	s_waitcnt vmcnt(4)
	v_or_b32_e32 v195, 0x2000, v3
	v_lshl_or_b32 v3, s10, 11, v4
	s_add_i32 s43, s11, 0
	v_lshl_or_b32 v2, v2, 3, s2
	v_mov_b32_e32 v50, 0
	s_mov_b32 s70, 0
	s_add_i32 s44, s43, 0xe000
	s_add_i32 s45, s43, 0x10000
	s_add_i32 s46, s43, 0x12000
	s_add_i32 s47, s43, 0x14000
	s_add_i32 s48, s43, 0x16000
	s_add_i32 s49, s43, 0x2000
	s_add_i32 s50, s43, 0x6000
	s_add_i32 s51, s43, 0x18000
	s_add_i32 s52, s43, 0x1a000
	s_add_i32 s53, s43, 0x1c000
	s_add_i32 s54, s43, 0x1e000
	s_add_i32 s55, s43, 0xa000
	s_add_i32 s56, s43, 0xd000
	s_add_i32 s57, s43, 0x11000
	s_add_i32 s58, s43, 0x15000
	s_add_i32 s59, s43, 0x1000
	s_add_i32 s60, s43, 0x5000
	s_add_i32 s61, s43, 0x19000
	s_add_i32 s62, s43, 0x1d000
	s_add_i32 s63, s43, 0x9000
	v_or_b32_e32 v196, 0x1400, v2
	s_add_i32 s64, s43, 0xc000
	s_add_i32 s65, s43, 0x4000
	s_add_i32 s66, s43, 0x8000
	s_mov_b32 s24, 0x3b800000
	s_mov_b32 s67, 0xcc00
	v_add_u32_e32 v197, 0, v5
	v_add_u32_e32 v198, 0, v3
	v_mov_b32_e32 v51, v50
	v_mov_b32_e32 v52, v50
	v_mov_b32_e32 v53, v50
	v_mov_b32_e32 v54, v50
	v_mov_b32_e32 v55, v50
	v_mov_b32_e32 v56, v50
	v_mov_b32_e32 v57, v50
	v_mov_b32_e32 v58, v50
	v_mov_b32_e32 v59, v50
	v_mov_b32_e32 v60, v50
	v_mov_b32_e32 v61, v50
	v_mov_b32_e32 v62, v50
	v_mov_b32_e32 v63, v50
	v_mov_b32_e32 v64, v50
	v_mov_b32_e32 v65, v50
	v_mov_b32_e32 v66, v50
	v_mov_b32_e32 v67, v50
	v_mov_b32_e32 v68, v50
	v_mov_b32_e32 v69, v50
	v_mov_b32_e32 v70, v50
	v_mov_b32_e32 v71, v50
	v_mov_b32_e32 v72, v50
	v_mov_b32_e32 v73, v50
	v_mov_b32_e32 v74, v50
	v_mov_b32_e32 v75, v50
	v_mov_b32_e32 v76, v50
	v_mov_b32_e32 v77, v50
	v_mov_b32_e32 v78, v50
	v_mov_b32_e32 v79, v50
	v_mov_b32_e32 v80, v50
	v_mov_b32_e32 v81, v50
	v_mov_b32_e32 v82, v50
	v_mov_b32_e32 v83, v50
	v_mov_b32_e32 v84, v50
	v_mov_b32_e32 v85, v50
	v_mov_b32_e32 v86, v50
	v_mov_b32_e32 v87, v50
	v_mov_b32_e32 v88, v50
	v_mov_b32_e32 v89, v50
	v_mov_b32_e32 v90, v50
	v_mov_b32_e32 v91, v50
	v_mov_b32_e32 v92, v50
	v_mov_b32_e32 v93, v50
	v_mov_b32_e32 v94, v50
	v_mov_b32_e32 v95, v50
	v_mov_b32_e32 v96, v50
	v_mov_b32_e32 v97, v50
	v_mov_b32_e32 v98, v50
	v_mov_b32_e32 v99, v50
	v_mov_b32_e32 v100, v50
	v_mov_b32_e32 v101, v50
	v_mov_b32_e32 v102, v50
	v_mov_b32_e32 v103, v50
	v_mov_b32_e32 v104, v50
	v_mov_b32_e32 v105, v50
	v_mov_b32_e32 v106, v50
	v_mov_b32_e32 v107, v50
	v_mov_b32_e32 v108, v50
	v_mov_b32_e32 v109, v50
	v_mov_b32_e32 v110, v50
	v_mov_b32_e32 v111, v50
	v_mov_b32_e32 v112, v50
	v_mov_b32_e32 v113, v50
	v_mov_b32_e32 v114, v50
	v_mov_b32_e32 v115, v50
	v_mov_b32_e32 v116, v50
	v_mov_b32_e32 v117, v50
	v_mov_b32_e32 v118, v50
	v_mov_b32_e32 v119, v50
	v_mov_b32_e32 v120, v50
	v_mov_b32_e32 v121, v50
	v_mov_b32_e32 v122, v50
	v_mov_b32_e32 v123, v50
	v_mov_b32_e32 v124, v50
	v_mov_b32_e32 v125, v50
	v_mov_b32_e32 v126, v50
	v_mov_b32_e32 v127, v50
	v_mov_b32_e32 v128, v50
	v_mov_b32_e32 v129, v50
	v_mov_b32_e32 v130, v50
	v_mov_b32_e32 v131, v50
	v_mov_b32_e32 v132, v50
	v_mov_b32_e32 v133, v50
	v_mov_b32_e32 v134, v50
	v_mov_b32_e32 v135, v50
	v_mov_b32_e32 v136, v50
	v_mov_b32_e32 v137, v50
	v_mov_b32_e32 v138, v50
	v_mov_b32_e32 v139, v50
	v_mov_b32_e32 v140, v50
	v_mov_b32_e32 v141, v50
	v_mov_b32_e32 v142, v50
	v_mov_b32_e32 v143, v50
	v_mov_b32_e32 v144, v50
	v_mov_b32_e32 v145, v50
	v_mov_b32_e32 v146, v50
	v_mov_b32_e32 v147, v50
	v_mov_b32_e32 v148, v50
	v_mov_b32_e32 v149, v50
	v_mov_b32_e32 v150, v50
	v_mov_b32_e32 v151, v50
	v_mov_b32_e32 v152, v50
	v_mov_b32_e32 v153, v50
	v_mov_b32_e32 v154, v50
	v_mov_b32_e32 v155, v50
	v_mov_b32_e32 v156, v50
	v_mov_b32_e32 v157, v50
	v_mov_b32_e32 v158, v50
	v_mov_b32_e32 v159, v50
	v_mov_b32_e32 v160, v50
	v_mov_b32_e32 v161, v50
	v_mov_b32_e32 v162, v50
	v_mov_b32_e32 v163, v50
	v_mov_b32_e32 v164, v50
	v_mov_b32_e32 v165, v50
	v_mov_b32_e32 v166, v50
	v_mov_b32_e32 v167, v50
	v_mov_b32_e32 v168, v50
	v_mov_b32_e32 v169, v50
	v_mov_b32_e32 v170, v50
	v_mov_b32_e32 v171, v50
	v_mov_b32_e32 v172, v50
	v_mov_b32_e32 v173, v50
	v_mov_b32_e32 v174, v50
	v_mov_b32_e32 v175, v50
	v_mov_b32_e32 v176, v50
	v_mov_b32_e32 v177, v50
	v_lshl_or_b32 v199, s10, 6, v193
	v_mov_b32_e32 v200, 0x7f7f7f7f
	v_mov_b64_e32 v[186:187], 0xa20
	v_mov_b64_e32 v[188:189], 0xa1f
	s_barrier
	s_mov_b32 s32, 1
	v_mov_b32_e32 v244, v180
	v_mov_b32_e32 v245, v182
	v_mov_b32_e32 v246, v184
	s_branch .LBB0_174

.LBB0_182:
	v_add_u32_e32 v247, 0x10000, v194
	v_add_u32_e32 v248, 0x10000, v195
	s_and_b64 vcc, exec, s[0:1]
	s_cbranch_vccz .Lsp1_in_L0
.Lsp0_in_L0:
	s_cmp_eq_u32 s32, 0
	s_cbranch_scc1 .Lsp0_rd_L0
	s_mov_b32 m0, s64
	s_nop 0
	global_load_lds_dwordx4 v244, s[2:3]
	s_mov_b32 m0, s56
	s_nop 0
	global_load_lds_dwordx4 v245, s[2:3]
	s_mov_b32 s32, 0
.Lsp0_rd_L0:
	ds_read_b128 v[44:47], v197
	ds_read_b64 v[48:49], v198 offset:8192
	ds_read_b128 v[38:41], v197 offset:1024
	ds_read_b64 v[42:43], v198 offset:8704
	ds_read_b128 v[32:35], v197 offset:2048
	ds_read_b64 v[36:37], v198 offset:9216
	ds_read_b128 v[26:29], v197 offset:3072
	ds_read_b64 v[30:31], v198 offset:9728
	ds_read_b128 v[20:23], v247
	ds_read_b64 v[24:25], v248
	ds_read_b128 v[14:17], v247 offset:1024
	ds_read_b64 v[18:19], v248 offset:512
	ds_read_b128 v[8:11], v247 offset:16384
	ds_read_b64 v[12:13], v248 offset:16384
	ds_read_b128 v[2:5], v247 offset:17408
	ds_read_b64 v[6:7], v248 offset:16896
	s_waitcnt lgkmcnt(0)
	s_barrier
.Lsp0_top_L0:
	s_add_u32 s34, s2, 0xfffa3000
	s_addc_u32 s35, s3, -1
	s_cmp_eq_u32 s73, 28
	s_cselect_b32 s28, s26, s33
	s_cselect_b32 s29, s27, s72
	s_cselect_b32 s30, s12, s34
	s_cselect_b32 s31, s13, s35
	s_add_u32 s34, s28, 0x60000
	s_addc_u32 s35, s29, 0
	s_mov_b32 m0, s49
	v_mfma_scale_f32_16x16x128_f8f6f4 v[174:177], v[20:25], v[44:49], v[174:177], v200, v200 op_sel_hi:[0,0,0] cbsz:2 blgp:2
	global_load_lds_dwordx4 v246, s[30:31]
	v_mfma_scale_f32_16x16x128_f8f6f4 v[170:173], v[14:19], v[44:49], v[170:173], v200, v200 op_sel_hi:[0,0,0] cbsz:2 blgp:2
	ds_read_b128 v[208:211], v197 offset:16384
	v_mfma_scale_f32_16x16x128_f8f6f4 v[166:169], v[20:25], v[38:43], v[166:169], v200, v200 op_sel_hi:[0,0,0] cbsz:2 blgp:2
	ds_read_b64 v[212:213], v198 offset:24576
	s_mov_b32 m0, s46
	v_mfma_scale_f32_16x16x128_f8f6f4 v[162:165], v[14:19], v[38:43], v[162:165], v200, v200 op_sel_hi:[0,0,0] cbsz:2 blgp:2
	global_load_lds_dwordx4 v246, s[28:29]
	v_mfma_scale_f32_16x16x128_f8f6f4 v[158:161], v[20:25], v[32:37], v[158:161], v200, v200 op_sel_hi:[0,0,0] cbsz:2 blgp:2
	ds_read_b128 v[214:217], v197 offset:17408
	v_mfma_scale_f32_16x16x128_f8f6f4 v[154:157], v[14:19], v[32:37], v[154:157], v200, v200 op_sel_hi:[0,0,0] cbsz:2 blgp:2
	ds_read_b64 v[218:219], v198 offset:25088
	s_mov_b32 m0, s47
	v_mfma_scale_f32_16x16x128_f8f6f4 v[150:153], v[20:25], v[26:31], v[150:153], v200, v200 op_sel_hi:[0,0,0] cbsz:2 blgp:2
	global_load_lds_dwordx4 v244, s[34:35]
	v_mfma_scale_f32_16x16x128_f8f6f4 v[146:149], v[14:19], v[26:31], v[146:149], v200, v200 op_sel_hi:[0,0,0] cbsz:2 blgp:2
	ds_read_b128 v[220:223], v197 offset:18432
	v_mfma_scale_f32_16x16x128_f8f6f4 v[142:145], v[8:13], v[44:49], v[142:145], v200, v200 op_sel_hi:[0,0,0] cbsz:2 blgp:2
	ds_read_b64 v[224:225], v198 offset:25600
	s_mov_b32 m0, s58
	v_mfma_scale_f32_16x16x128_f8f6f4 v[138:141], v[2:7], v[44:49], v[138:141], v200, v200 op_sel_hi:[0,0,0] cbsz:2 blgp:2
	global_load_lds_dwordx4 v245, s[34:35]
	v_mfma_scale_f32_16x16x128_f8f6f4 v[134:137], v[8:13], v[38:43], v[134:137], v200, v200 op_sel_hi:[0,0,0] cbsz:2 blgp:2
	ds_read_b128 v[226:229], v197 offset:19456
	v_mfma_scale_f32_16x16x128_f8f6f4 v[130:133], v[2:7], v[38:43], v[130:133], v200, v200 op_sel_hi:[0,0,0] cbsz:2 blgp:2
	ds_read_b64 v[230:231], v198 offset:26112
	v_mfma_scale_f32_16x16x128_f8f6f4 v[126:129], v[8:13], v[32:37], v[126:129], v200, v200 op_sel_hi:[0,0,0] cbsz:2 blgp:2
	v_mfma_scale_f32_16x16x128_f8f6f4 v[122:125], v[2:7], v[32:37], v[122:125], v200, v200 op_sel_hi:[0,0,0] cbsz:2 blgp:2
	v_mfma_scale_f32_16x16x128_f8f6f4 v[118:121], v[8:13], v[26:31], v[118:121], v200, v200 op_sel_hi:[0,0,0] cbsz:2 blgp:2
	v_mfma_scale_f32_16x16x128_f8f6f4 v[114:117], v[2:7], v[26:31], v[114:117], v200, v200 op_sel_hi:[0,0,0] cbsz:2 blgp:2
	s_waitcnt vmcnt(6)
	s_waitcnt lgkmcnt(0)
	s_barrier
	s_add_u32 s34, s30, 0x60000
	s_addc_u32 s35, s31, 0
	s_mov_b32 m0, s65
	v_mfma_scale_f32_16x16x128_f8f6f4 v[110:113], v[20:25], v[208:213], v[110:113], v200, v200 op_sel_hi:[0,0,0] cbsz:2 blgp:2
	global_load_lds_dwordx4 v244, s[34:35]
	ds_read_b128 v[44:47], v197 offset:32768
	s_mov_b32 m0, s60
	v_mfma_scale_f32_16x16x128_f8f6f4 v[106:109], v[14:19], v[208:213], v[106:109], v200, v200 op_sel_hi:[0,0,0] cbsz:2 blgp:2
	ds_read_b64 v[48:49], v198 offset:40960
	global_load_lds_dwordx4 v245, s[34:35]
	v_mfma_scale_f32_16x16x128_f8f6f4 v[102:105], v[20:25], v[214:219], v[102:105], v200, v200 op_sel_hi:[0,0,0] cbsz:2 blgp:2
	ds_read_b128 v[38:41], v197 offset:33792
	ds_read_b64 v[42:43], v198 offset:41472
	v_mfma_scale_f32_16x16x128_f8f6f4 v[98:101], v[14:19], v[214:219], v[98:101], v200, v200 op_sel_hi:[0,0,0] cbsz:2 blgp:2
	ds_read_b128 v[32:35], v197 offset:34816
	ds_read_b64 v[36:37], v198 offset:41984
	v_mfma_scale_f32_16x16x128_f8f6f4 v[94:97], v[20:25], v[220:225], v[94:97], v200, v200 op_sel_hi:[0,0,0] cbsz:2 blgp:2
	ds_read_b128 v[26:29], v197 offset:35840
	ds_read_b64 v[30:31], v198 offset:42496
	v_mfma_scale_f32_16x16x128_f8f6f4 v[90:93], v[14:19], v[220:225], v[90:93], v200, v200 op_sel_hi:[0,0,0] cbsz:2 blgp:2
	ds_read_b128 v[232:235], v247 offset:32768
	ds_read_b64 v[236:237], v248 offset:32768
	v_mfma_scale_f32_16x16x128_f8f6f4 v[86:89], v[20:25], v[226:231], v[86:89], v200, v200 op_sel_hi:[0,0,0] cbsz:2 blgp:2
	ds_read_b128 v[238:241], v247 offset:33792
	ds_read_b64 v[242:243], v248 offset:33280
	v_mfma_scale_f32_16x16x128_f8f6f4 v[82:85], v[14:19], v[226:231], v[82:85], v200, v200 op_sel_hi:[0,0,0] cbsz:2 blgp:2
	ds_read_b128 v[180:183], v247 offset:49152
	ds_read_b64 v[184:185], v248 offset:49152
	v_mfma_scale_f32_16x16x128_f8f6f4 v[78:81], v[8:13], v[208:213], v[78:81], v200, v200 op_sel_hi:[0,0,0] cbsz:2 blgp:2
	ds_read_b128 v[250:253], v247 offset:50176
	ds_read_b64 v[254:255], v248 offset:49664
	v_mfma_scale_f32_16x16x128_f8f6f4 v[74:77], v[2:7], v[208:213], v[74:77], v200, v200 op_sel_hi:[0,0,0] cbsz:2 blgp:2
	v_mfma_scale_f32_16x16x128_f8f6f4 v[70:73], v[8:13], v[214:219], v[70:73], v200, v200 op_sel_hi:[0,0,0] cbsz:2 blgp:2
	v_mfma_scale_f32_16x16x128_f8f6f4 v[66:69], v[2:7], v[214:219], v[66:69], v200, v200 op_sel_hi:[0,0,0] cbsz:2 blgp:2
	v_mfma_scale_f32_16x16x128_f8f6f4 v[62:65], v[8:13], v[220:225], v[62:65], v200, v200 op_sel_hi:[0,0,0] cbsz:2 blgp:2
	v_mfma_scale_f32_16x16x128_f8f6f4 v[58:61], v[2:7], v[220:225], v[58:61], v200, v200 op_sel_hi:[0,0,0] cbsz:2 blgp:2
	v_mfma_scale_f32_16x16x128_f8f6f4 v[54:57], v[8:13], v[226:231], v[54:57], v200, v200 op_sel_hi:[0,0,0] cbsz:2 blgp:2
	v_mfma_scale_f32_16x16x128_f8f6f4 v[50:53], v[2:7], v[226:231], v[50:53], v200, v200 op_sel_hi:[0,0,0] cbsz:2 blgp:2
	s_waitcnt vmcnt(6)
	s_waitcnt lgkmcnt(0)
	s_barrier
	s_add_u32 s30, s30, 0x3000
	s_addc_u32 s31, s31, 0
	s_add_u32 s28, s28, 0x3000
	s_addc_u32 s29, s29, 0
	s_add_u32 s34, s28, 0x60000
	s_addc_u32 s35, s29, 0
	s_mov_b32 m0, s55
	v_mfma_scale_f32_16x16x128_f8f6f4 v[174:177], v[232:237], v[44:49], v[174:177], v200, v200 op_sel_hi:[0,0,0] cbsz:2 blgp:2
	global_load_lds_dwordx4 v246, s[30:31]
	v_mfma_scale_f32_16x16x128_f8f6f4 v[170:173], v[238:243], v[44:49], v[170:173], v200, v200 op_sel_hi:[0,0,0] cbsz:2 blgp:2
	ds_read_b128 v[208:211], v197 offset:49152
	v_mfma_scale_f32_16x16x128_f8f6f4 v[166:169], v[232:237], v[38:43], v[166:169], v200, v200 op_sel_hi:[0,0,0] cbsz:2 blgp:2
	ds_read_b64 v[212:213], v198 offset:57344
	s_mov_b32 m0, s52
	v_mfma_scale_f32_16x16x128_f8f6f4 v[162:165], v[238:243], v[38:43], v[162:165], v200, v200 op_sel_hi:[0,0,0] cbsz:2 blgp:2
	global_load_lds_dwordx4 v246, s[28:29]
	v_mfma_scale_f32_16x16x128_f8f6f4 v[158:161], v[232:237], v[32:37], v[158:161], v200, v200 op_sel_hi:[0,0,0] cbsz:2 blgp:2
	ds_read_b128 v[214:217], v197 offset:50176
	v_mfma_scale_f32_16x16x128_f8f6f4 v[154:157], v[238:243], v[32:37], v[154:157], v200, v200 op_sel_hi:[0,0,0] cbsz:2 blgp:2
	ds_read_b64 v[218:219], v198 offset:57856
	s_mov_b32 m0, s53
	v_mfma_scale_f32_16x16x128_f8f6f4 v[150:153], v[232:237], v[26:31], v[150:153], v200, v200 op_sel_hi:[0,0,0] cbsz:2 blgp:2
	global_load_lds_dwordx4 v244, s[34:35]
	v_mfma_scale_f32_16x16x128_f8f6f4 v[146:149], v[238:243], v[26:31], v[146:149], v200, v200 op_sel_hi:[0,0,0] cbsz:2 blgp:2
	ds_read_b128 v[220:223], v197 offset:51200
	v_mfma_scale_f32_16x16x128_f8f6f4 v[142:145], v[180:185], v[44:49], v[142:145], v200, v200 op_sel_hi:[0,0,0] cbsz:2 blgp:2
	ds_read_b64 v[224:225], v198 offset:58368
	s_mov_b32 m0, s62
	v_mfma_scale_f32_16x16x128_f8f6f4 v[138:141], v[250:255], v[44:49], v[138:141], v200, v200 op_sel_hi:[0,0,0] cbsz:2 blgp:2
	global_load_lds_dwordx4 v245, s[34:35]
	v_mfma_scale_f32_16x16x128_f8f6f4 v[134:137], v[180:185], v[38:43], v[134:137], v200, v200 op_sel_hi:[0,0,0] cbsz:2 blgp:2
	ds_read_b128 v[226:229], v197 offset:52224
	v_mfma_scale_f32_16x16x128_f8f6f4 v[130:133], v[250:255], v[38:43], v[130:133], v200, v200 op_sel_hi:[0,0,0] cbsz:2 blgp:2
	ds_read_b64 v[230:231], v198 offset:58880
	v_mfma_scale_f32_16x16x128_f8f6f4 v[126:129], v[180:185], v[32:37], v[126:129], v200, v200 op_sel_hi:[0,0,0] cbsz:2 blgp:2
	v_mfma_scale_f32_16x16x128_f8f6f4 v[122:125], v[250:255], v[32:37], v[122:125], v200, v200 op_sel_hi:[0,0,0] cbsz:2 blgp:2
	v_mfma_scale_f32_16x16x128_f8f6f4 v[118:121], v[180:185], v[26:31], v[118:121], v200, v200 op_sel_hi:[0,0,0] cbsz:2 blgp:2
	v_mfma_scale_f32_16x16x128_f8f6f4 v[114:117], v[250:255], v[26:31], v[114:117], v200, v200 op_sel_hi:[0,0,0] cbsz:2 blgp:2
	s_waitcnt vmcnt(6)
	s_waitcnt lgkmcnt(0)
	s_barrier
	s_add_u32 s34, s30, 0x60000
	s_addc_u32 s35, s31, 0
	s_mov_b32 m0, s64
	v_mfma_scale_f32_16x16x128_f8f6f4 v[110:113], v[232:237], v[208:213], v[110:113], v200, v200 op_sel_hi:[0,0,0] cbsz:2 blgp:2
	global_load_lds_dwordx4 v244, s[34:35]
	ds_read_b128 v[44:47], v197
	s_mov_b32 m0, s56
	v_mfma_scale_f32_16x16x128_f8f6f4 v[106:109], v[238:243], v[208:213], v[106:109], v200, v200 op_sel_hi:[0,0,0] cbsz:2 blgp:2
	ds_read_b64 v[48:49], v198 offset:8192
	global_load_lds_dwordx4 v245, s[34:35]
	v_mfma_scale_f32_16x16x128_f8f6f4 v[102:105], v[232:237], v[214:219], v[102:105], v200, v200 op_sel_hi:[0,0,0] cbsz:2 blgp:2
	ds_read_b128 v[38:41], v197 offset:1024
	ds_read_b64 v[42:43], v198 offset:8704
	v_mfma_scale_f32_16x16x128_f8f6f4 v[98:101], v[238:243], v[214:219], v[98:101], v200, v200 op_sel_hi:[0,0,0] cbsz:2 blgp:2
	ds_read_b128 v[32:35], v197 offset:2048
	ds_read_b64 v[36:37], v198 offset:9216
	v_mfma_scale_f32_16x16x128_f8f6f4 v[94:97], v[232:237], v[220:225], v[94:97], v200, v200 op_sel_hi:[0,0,0] cbsz:2 blgp:2
	ds_read_b128 v[26:29], v197 offset:3072
	ds_read_b64 v[30:31], v198 offset:9728
	v_mfma_scale_f32_16x16x128_f8f6f4 v[90:93], v[238:243], v[220:225], v[90:93], v200, v200 op_sel_hi:[0,0,0] cbsz:2 blgp:2
	ds_read_b128 v[20:23], v247
	ds_read_b64 v[24:25], v248
	v_mfma_scale_f32_16x16x128_f8f6f4 v[86:89], v[232:237], v[226:231], v[86:89], v200, v200 op_sel_hi:[0,0,0] cbsz:2 blgp:2
	ds_read_b128 v[14:17], v247 offset:1024
	ds_read_b64 v[18:19], v248 offset:512
	v_mfma_scale_f32_16x16x128_f8f6f4 v[82:85], v[238:243], v[226:231], v[82:85], v200, v200 op_sel_hi:[0,0,0] cbsz:2 blgp:2
	ds_read_b128 v[8:11], v247 offset:16384
	ds_read_b64 v[12:13], v248 offset:16384
	v_mfma_scale_f32_16x16x128_f8f6f4 v[78:81], v[180:185], v[208:213], v[78:81], v200, v200 op_sel_hi:[0,0,0] cbsz:2 blgp:2
	ds_read_b128 v[2:5], v247 offset:17408
	ds_read_b64 v[6:7], v248 offset:16896
	v_mfma_scale_f32_16x16x128_f8f6f4 v[74:77], v[250:255], v[208:213], v[74:77], v200, v200 op_sel_hi:[0,0,0] cbsz:2 blgp:2
	v_mfma_scale_f32_16x16x128_f8f6f4 v[70:73], v[180:185], v[214:219], v[70:73], v200, v200 op_sel_hi:[0,0,0] cbsz:2 blgp:2
	v_mfma_scale_f32_16x16x128_f8f6f4 v[66:69], v[250:255], v[214:219], v[66:69], v200, v200 op_sel_hi:[0,0,0] cbsz:2 blgp:2
	v_mfma_scale_f32_16x16x128_f8f6f4 v[62:65], v[180:185], v[220:225], v[62:65], v200, v200 op_sel_hi:[0,0,0] cbsz:2 blgp:2
	v_mfma_scale_f32_16x16x128_f8f6f4 v[58:61], v[250:255], v[220:225], v[58:61], v200, v200 op_sel_hi:[0,0,0] cbsz:2 blgp:2
	v_mfma_scale_f32_16x16x128_f8f6f4 v[54:57], v[180:185], v[226:231], v[54:57], v200, v200 op_sel_hi:[0,0,0] cbsz:2 blgp:2
	v_mfma_scale_f32_16x16x128_f8f6f4 v[50:53], v[250:255], v[226:231], v[50:53], v200, v200 op_sel_hi:[0,0,0] cbsz:2 blgp:2
	s_waitcnt vmcnt(6)
	s_waitcnt lgkmcnt(0)
	s_barrier
	s_add_i32 s73, s73, 2
	s_add_u32 s2, s2, 0x6000
	s_addc_u32 s3, s3, 0
	s_add_u32 s33, s33, 0x6000
	s_addc_u32 s72, s72, 0
	s_cmp_gt_u32 s73, 29
	s_cbranch_scc0 .Lsp0_top_L0
	s_branch .LBB0_198
.Lsp1_in_L0:
	s_cmp_eq_u32 s32, 0
	s_cbranch_scc1 .Lsp1_rd_L0
	s_mov_b32 m0, s44
	s_nop 0
	global_load_lds_dwordx4 v246, s[2:3]
	s_mov_b32 s32, 0

.Lsp1_top_L0:
	s_add_u32 s34, s2, 0xfffa3000
	s_addc_u32 s35, s3, -1
	s_cmp_eq_u32 s73, 28
	s_cselect_b32 s28, s26, s33
	s_cselect_b32 s29, s27, s72
	s_cselect_b32 s30, s12, s34
	s_cselect_b32 s31, s13, s35
	s_add_u32 s34, s28, 0x60000
	s_addc_u32 s35, s29, 0
	s_mov_b32 m0, s43
	v_mfma_scale_f32_16x16x128_f8f6f4 v[174:177], v[20:25], v[44:49], v[174:177], v200, v200 op_sel_hi:[0,0,0] cbsz:2 blgp:2
	global_load_lds_dwordx4 v244, s[30:31]
	v_mfma_scale_f32_16x16x128_f8f6f4 v[170:173], v[14:19], v[44:49], v[170:173], v200, v200 op_sel_hi:[0,0,0] cbsz:2 blgp:2
	ds_read_b128 v[208:211], v197 offset:16384
	v_mfma_scale_f32_16x16x128_f8f6f4 v[166:169], v[20:25], v[38:43], v[166:169], v200, v200 op_sel_hi:[0,0,0] cbsz:2 blgp:2
	ds_read_b64 v[212:213], v198 offset:24576
	s_mov_b32 m0, s59
	v_mfma_scale_f32_16x16x128_f8f6f4 v[162:165], v[14:19], v[38:43], v[162:165], v200, v200 op_sel_hi:[0,0,0] cbsz:2 blgp:2
	global_load_lds_dwordx4 v245, s[30:31]
	v_mfma_scale_f32_16x16x128_f8f6f4 v[158:161], v[20:25], v[32:37], v[158:161], v200, v200 op_sel_hi:[0,0,0] cbsz:2 blgp:2
	ds_read_b128 v[214:217], v197 offset:17408
	v_mfma_scale_f32_16x16x128_f8f6f4 v[154:157], v[14:19], v[32:37], v[154:157], v200, v200 op_sel_hi:[0,0,0] cbsz:2 blgp:2
	ds_read_b64 v[218:219], v198 offset:25088
	s_mov_b32 m0, s45
	v_mfma_scale_f32_16x16x128_f8f6f4 v[150:153], v[20:25], v[26:31], v[150:153], v200, v200 op_sel_hi:[0,0,0] cbsz:2 blgp:2
	global_load_lds_dwordx4 v244, s[28:29]
	v_mfma_scale_f32_16x16x128_f8f6f4 v[146:149], v[14:19], v[26:31], v[146:149], v200, v200 op_sel_hi:[0,0,0] cbsz:2 blgp:2
	ds_read_b128 v[220:223], v197 offset:18432
	v_mfma_scale_f32_16x16x128_f8f6f4 v[142:145], v[8:13], v[44:49], v[142:145], v200, v200 op_sel_hi:[0,0,0] cbsz:2 blgp:2
	ds_read_b64 v[224:225], v198 offset:25600
	s_mov_b32 m0, s57
	v_mfma_scale_f32_16x16x128_f8f6f4 v[138:141], v[2:7], v[44:49], v[138:141], v200, v200 op_sel_hi:[0,0,0] cbsz:2 blgp:2
	global_load_lds_dwordx4 v245, s[28:29]
	v_mfma_scale_f32_16x16x128_f8f6f4 v[134:137], v[8:13], v[38:43], v[134:137], v200, v200 op_sel_hi:[0,0,0] cbsz:2 blgp:2
	ds_read_b128 v[226:229], v197 offset:19456
	v_mfma_scale_f32_16x16x128_f8f6f4 v[130:133], v[2:7], v[38:43], v[130:133], v200, v200 op_sel_hi:[0,0,0] cbsz:2 blgp:2
	ds_read_b64 v[230:231], v198 offset:26112
	s_mov_b32 m0, s48
	v_mfma_scale_f32_16x16x128_f8f6f4 v[126:129], v[8:13], v[32:37], v[126:129], v200, v200 op_sel_hi:[0,0,0] cbsz:2 blgp:2
	global_load_lds_dwordx4 v246, s[34:35]
	v_mfma_scale_f32_16x16x128_f8f6f4 v[122:125], v[2:7], v[32:37], v[122:125], v200, v200 op_sel_hi:[0,0,0] cbsz:2 blgp:2
	v_mfma_scale_f32_16x16x128_f8f6f4 v[118:121], v[8:13], v[26:31], v[118:121], v200, v200 op_sel_hi:[0,0,0] cbsz:2 blgp:2
	v_mfma_scale_f32_16x16x128_f8f6f4 v[114:117], v[2:7], v[26:31], v[114:117], v200, v200 op_sel_hi:[0,0,0] cbsz:2 blgp:2
	s_waitcnt vmcnt(6)
	s_waitcnt lgkmcnt(0)
	s_barrier
	s_add_u32 s34, s30, 0x60000
	s_addc_u32 s35, s31, 0
	s_mov_b32 m0, s50
	v_mfma_scale_f32_16x16x128_f8f6f4 v[110:113], v[20:25], v[208:213], v[110:113], v200, v200 op_sel_hi:[0,0,0] cbsz:2 blgp:2
	global_load_lds_dwordx4 v246, s[34:35]
	ds_read_b128 v[44:47], v197 offset:32768
	v_mfma_scale_f32_16x16x128_f8f6f4 v[106:109], v[14:19], v[208:213], v[106:109], v200, v200 op_sel_hi:[0,0,0] cbsz:2 blgp:2
	ds_read_b64 v[48:49], v198 offset:40960
	ds_read_b128 v[38:41], v197 offset:33792
	v_mfma_scale_f32_16x16x128_f8f6f4 v[102:105], v[20:25], v[214:219], v[102:105], v200, v200 op_sel_hi:[0,0,0] cbsz:2 blgp:2
	ds_read_b64 v[42:43], v198 offset:41472
	ds_read_b128 v[32:35], v197 offset:34816
	v_mfma_scale_f32_16x16x128_f8f6f4 v[98:101], v[14:19], v[214:219], v[98:101], v200, v200 op_sel_hi:[0,0,0] cbsz:2 blgp:2
	ds_read_b64 v[36:37], v198 offset:41984
	ds_read_b128 v[26:29], v197 offset:35840
	v_mfma_scale_f32_16x16x128_f8f6f4 v[94:97], v[20:25], v[220:225], v[94:97], v200, v200 op_sel_hi:[0,0,0] cbsz:2 blgp:2
	ds_read_b64 v[30:31], v198 offset:42496
	ds_read_b128 v[232:235], v247 offset:32768
	v_mfma_scale_f32_16x16x128_f8f6f4 v[90:93], v[14:19], v[220:225], v[90:93], v200, v200 op_sel_hi:[0,0,0] cbsz:2 blgp:2
	ds_read_b64 v[236:237], v248 offset:32768
	ds_read_b128 v[238:241], v247 offset:33792
	v_mfma_scale_f32_16x16x128_f8f6f4 v[86:89], v[20:25], v[226:231], v[86:89], v200, v200 op_sel_hi:[0,0,0] cbsz:2 blgp:2
	ds_read_b64 v[242:243], v248 offset:33280
	ds_read_b128 v[180:183], v247 offset:49152
	v_mfma_scale_f32_16x16x128_f8f6f4 v[82:85], v[14:19], v[226:231], v[82:85], v200, v200 op_sel_hi:[0,0,0] cbsz:2 blgp:2
	ds_read_b64 v[184:185], v248 offset:49152
	ds_read_b128 v[250:253], v247 offset:50176
	v_mfma_scale_f32_16x16x128_f8f6f4 v[78:81], v[8:13], v[208:213], v[78:81], v200, v200 op_sel_hi:[0,0,0] cbsz:2 blgp:2
	ds_read_b64 v[254:255], v248 offset:49664
	v_mfma_scale_f32_16x16x128_f8f6f4 v[74:77], v[2:7], v[208:213], v[74:77], v200, v200 op_sel_hi:[0,0,0] cbsz:2 blgp:2
	v_mfma_scale_f32_16x16x128_f8f6f4 v[70:73], v[8:13], v[214:219], v[70:73], v200, v200 op_sel_hi:[0,0,0] cbsz:2 blgp:2
	v_mfma_scale_f32_16x16x128_f8f6f4 v[66:69], v[2:7], v[214:219], v[66:69], v200, v200 op_sel_hi:[0,0,0] cbsz:2 blgp:2
	v_mfma_scale_f32_16x16x128_f8f6f4 v[62:65], v[8:13], v[220:225], v[62:65], v200, v200 op_sel_hi:[0,0,0] cbsz:2 blgp:2
	v_mfma_scale_f32_16x16x128_f8f6f4 v[58:61], v[2:7], v[220:225], v[58:61], v200, v200 op_sel_hi:[0,0,0] cbsz:2 blgp:2
	v_mfma_scale_f32_16x16x128_f8f6f4 v[54:57], v[8:13], v[226:231], v[54:57], v200, v200 op_sel_hi:[0,0,0] cbsz:2 blgp:2
	v_mfma_scale_f32_16x16x128_f8f6f4 v[50:53], v[2:7], v[226:231], v[50:53], v200, v200 op_sel_hi:[0,0,0] cbsz:2 blgp:2
	s_waitcnt vmcnt(6)
	s_waitcnt lgkmcnt(0)
	s_barrier
	s_add_u32 s30, s30, 0x3000
	s_addc_u32 s31, s31, 0
	s_add_u32 s28, s28, 0x3000
	s_addc_u32 s29, s29, 0
	s_add_u32 s34, s28, 0x60000
	s_addc_u32 s35, s29, 0
	s_mov_b32 m0, s66
	v_mfma_scale_f32_16x16x128_f8f6f4 v[174:177], v[232:237], v[44:49], v[174:177], v200, v200 op_sel_hi:[0,0,0] cbsz:2 blgp:2
	global_load_lds_dwordx4 v244, s[30:31]
	v_mfma_scale_f32_16x16x128_f8f6f4 v[170:173], v[238:243], v[44:49], v[170:173], v200, v200 op_sel_hi:[0,0,0] cbsz:2 blgp:2
	ds_read_b128 v[208:211], v197 offset:49152
	v_mfma_scale_f32_16x16x128_f8f6f4 v[166:169], v[232:237], v[38:43], v[166:169], v200, v200 op_sel_hi:[0,0,0] cbsz:2 blgp:2
	ds_read_b64 v[212:213], v198 offset:57344
	s_mov_b32 m0, s63
	v_mfma_scale_f32_16x16x128_f8f6f4 v[162:165], v[238:243], v[38:43], v[162:165], v200, v200 op_sel_hi:[0,0,0] cbsz:2 blgp:2
	global_load_lds_dwordx4 v245, s[30:31]
	v_mfma_scale_f32_16x16x128_f8f6f4 v[158:161], v[232:237], v[32:37], v[158:161], v200, v200 op_sel_hi:[0,0,0] cbsz:2 blgp:2
	ds_read_b128 v[214:217], v197 offset:50176
	v_mfma_scale_f32_16x16x128_f8f6f4 v[154:157], v[238:243], v[32:37], v[154:157], v200, v200 op_sel_hi:[0,0,0] cbsz:2 blgp:2
	ds_read_b64 v[218:219], v198 offset:57856
	s_mov_b32 m0, s51
	v_mfma_scale_f32_16x16x128_f8f6f4 v[150:153], v[232:237], v[26:31], v[150:153], v200, v200 op_sel_hi:[0,0,0] cbsz:2 blgp:2
	global_load_lds_dwordx4 v244, s[28:29]
	v_mfma_scale_f32_16x16x128_f8f6f4 v[146:149], v[238:243], v[26:31], v[146:149], v200, v200 op_sel_hi:[0,0,0] cbsz:2 blgp:2
	ds_read_b128 v[220:223], v197 offset:51200
	v_mfma_scale_f32_16x16x128_f8f6f4 v[142:145], v[180:185], v[44:49], v[142:145], v200, v200 op_sel_hi:[0,0,0] cbsz:2 blgp:2
	ds_read_b64 v[224:225], v198 offset:58368
	s_mov_b32 m0, s61
	v_mfma_scale_f32_16x16x128_f8f6f4 v[138:141], v[250:255], v[44:49], v[138:141], v200, v200 op_sel_hi:[0,0,0] cbsz:2 blgp:2
	global_load_lds_dwordx4 v245, s[28:29]
	v_mfma_scale_f32_16x16x128_f8f6f4 v[134:137], v[180:185], v[38:43], v[134:137], v200, v200 op_sel_hi:[0,0,0] cbsz:2 blgp:2
	ds_read_b128 v[226:229], v197 offset:52224
	v_mfma_scale_f32_16x16x128_f8f6f4 v[130:133], v[250:255], v[38:43], v[130:133], v200, v200 op_sel_hi:[0,0,0] cbsz:2 blgp:2
	ds_read_b64 v[230:231], v198 offset:58880
	s_mov_b32 m0, s54
	v_mfma_scale_f32_16x16x128_f8f6f4 v[126:129], v[180:185], v[32:37], v[126:129], v200, v200 op_sel_hi:[0,0,0] cbsz:2 blgp:2
	global_load_lds_dwordx4 v246, s[34:35]
	v_mfma_scale_f32_16x16x128_f8f6f4 v[122:125], v[250:255], v[32:37], v[122:125], v200, v200 op_sel_hi:[0,0,0] cbsz:2 blgp:2
	v_mfma_scale_f32_16x16x128_f8f6f4 v[118:121], v[180:185], v[26:31], v[118:121], v200, v200 op_sel_hi:[0,0,0] cbsz:2 blgp:2
	v_mfma_scale_f32_16x16x128_f8f6f4 v[114:117], v[250:255], v[26:31], v[114:117], v200, v200 op_sel_hi:[0,0,0] cbsz:2 blgp:2
	s_waitcnt vmcnt(6)
	s_waitcnt lgkmcnt(0)
	s_barrier
	s_add_u32 s34, s30, 0x60000
	s_addc_u32 s35, s31, 0
	s_mov_b32 m0, s44
	v_mfma_scale_f32_16x16x128_f8f6f4 v[110:113], v[232:237], v[208:213], v[110:113], v200, v200 op_sel_hi:[0,0,0] cbsz:2 blgp:2
	global_load_lds_dwordx4 v246, s[34:35]
	ds_read_b128 v[44:47], v197
	v_mfma_scale_f32_16x16x128_f8f6f4 v[106:109], v[238:243], v[208:213], v[106:109], v200, v200 op_sel_hi:[0,0,0] cbsz:2 blgp:2
	ds_read_b64 v[48:49], v198 offset:8192
	ds_read_b128 v[38:41], v197 offset:1024
	v_mfma_scale_f32_16x16x128_f8f6f4 v[102:105], v[232:237], v[214:219], v[102:105], v200, v200 op_sel_hi:[0,0,0] cbsz:2 blgp:2
	ds_read_b64 v[42:43], v198 offset:8704
	ds_read_b128 v[32:35], v197 offset:2048
	v_mfma_scale_f32_16x16x128_f8f6f4 v[98:101], v[238:243], v[214:219], v[98:101], v200, v200 op_sel_hi:[0,0,0] cbsz:2 blgp:2
	ds_read_b64 v[36:37], v198 offset:9216
	ds_read_b128 v[26:29], v197 offset:3072
	v_mfma_scale_f32_16x16x128_f8f6f4 v[94:97], v[232:237], v[220:225], v[94:97], v200, v200 op_sel_hi:[0,0,0] cbsz:2 blgp:2
	ds_read_b64 v[30:31], v198 offset:9728
	ds_read_b128 v[20:23], v247
	v_mfma_scale_f32_16x16x128_f8f6f4 v[90:93], v[238:243], v[220:225], v[90:93], v200, v200 op_sel_hi:[0,0,0] cbsz:2 blgp:2
	ds_read_b64 v[24:25], v248
	ds_read_b128 v[14:17], v247 offset:1024
	v_mfma_scale_f32_16x16x128_f8f6f4 v[86:89], v[232:237], v[226:231], v[86:89], v200, v200 op_sel_hi:[0,0,0] cbsz:2 blgp:2
	ds_read_b64 v[18:19], v248 offset:512
	ds_read_b128 v[8:11], v247 offset:16384
	v_mfma_scale_f32_16x16x128_f8f6f4 v[82:85], v[238:243], v[226:231], v[82:85], v200, v200 op_sel_hi:[0,0,0] cbsz:2 blgp:2
	ds_read_b64 v[12:13], v248 offset:16384
	ds_read_b128 v[2:5], v247 offset:17408
	v_mfma_scale_f32_16x16x128_f8f6f4 v[78:81], v[180:185], v[208:213], v[78:81], v200, v200 op_sel_hi:[0,0,0] cbsz:2 blgp:2
	ds_read_b64 v[6:7], v248 offset:16896
	v_mfma_scale_f32_16x16x128_f8f6f4 v[74:77], v[250:255], v[208:213], v[74:77], v200, v200 op_sel_hi:[0,0,0] cbsz:2 blgp:2
	v_mfma_scale_f32_16x16x128_f8f6f4 v[70:73], v[180:185], v[214:219], v[70:73], v200, v200 op_sel_hi:[0,0,0] cbsz:2 blgp:2
	v_mfma_scale_f32_16x16x128_f8f6f4 v[66:69], v[250:255], v[214:219], v[66:69], v200, v200 op_sel_hi:[0,0,0] cbsz:2 blgp:2
	v_mfma_scale_f32_16x16x128_f8f6f4 v[62:65], v[180:185], v[220:225], v[62:65], v200, v200 op_sel_hi:[0,0,0] cbsz:2 blgp:2
	v_mfma_scale_f32_16x16x128_f8f6f4 v[58:61], v[250:255], v[220:225], v[58:61], v200, v200 op_sel_hi:[0,0,0] cbsz:2 blgp:2
	v_mfma_scale_f32_16x16x128_f8f6f4 v[54:57], v[180:185], v[226:231], v[54:57], v200, v200 op_sel_hi:[0,0,0] cbsz:2 blgp:2
	v_mfma_scale_f32_16x16x128_f8f6f4 v[50:53], v[250:255], v[226:231], v[50:53], v200, v200 op_sel_hi:[0,0,0] cbsz:2 blgp:2
	s_waitcnt vmcnt(6)
	s_waitcnt lgkmcnt(0)
	s_barrier
	s_add_i32 s73, s73, 2
	s_add_u32 s2, s2, 0x6000
	s_addc_u32 s3, s3, 0
	s_add_u32 s33, s33, 0x6000
	s_addc_u32 s72, s72, 0
	s_cmp_gt_u32 s73, 29
	s_cbranch_scc0 .Lsp1_top_L0
	s_branch .LBB0_198
.LBB0_198:
	s_nop 15
	s_nop 15
	s_and_b64 vcc, exec, s[18:19]
	s_cbranch_vccz .LBB0_200
	s_nop 0

.LBB0_312:
	v_cvt_pk_bf16_f32 v4, v4, v5
	v_cvt_pk_bf16_f32 v5, v8, v9
	v_cvt_pk_bf16_f32 v6, v6, v7
	v_cvt_pk_bf16_f32 v7, v10, v11
	s_and_b64 vcc, exec, s[10:11]
	global_store_dwordx4 v[2:3], v[4:7], off offset:256
	s_cbranch_vccnz .LBB0_173
	s_and_b64 vcc, exec, s[6:7]
	s_cbranch_vccnz .LBB0_172
	s_nop 0
	s_branch .LBB0_172

.LBB0_949:
	v_cndmask_b32_e64 v2, 0, 1, s[2:3]
	v_cmp_ne_u32_e64 s[8:9], 1, v2
	s_andn2_b64 vcc, exec, s[2:3]
	s_cbranch_vccnz .LBB0_951
.LBB0_950:
	s_nop 0
.LBB0_951:
	s_waitcnt vmcnt(1)
	s_add_u32 s2, s20, 0x3000
	s_addc_u32 s3, s21, 0
	s_and_b64 vcc, exec, s[4:5]
	s_mov_b64 s[10:11], -1
	s_barrier
	s_cbranch_vccnz .LBB0_953
	s_add_i32 s10, s12, 0
	s_add_i32 m0, s10, 0x18000
	s_nop 0
	global_load_lds_dwordx4 v180, s[2:3]
	s_add_i32 m0, s10, 0x19000
	s_mov_b64 s[10:11], 0
	global_load_lds_dwordx4 v182, s[2:3]

.LBB0_965:
	v_and_b32_e32 v3, 48, v0
	v_lshrrev_b32_e32 v2, 4, v178
	v_lshl_or_b32 v3, v199, 6, v3
	v_lshlrev_b32_e32 v4, 3, v199
	s_lshl_b32 s2, s14, 12
	v_lshl_or_b32 v4, v2, 7, v4
	v_bitop3_b32 v5, s2, v3, v1 bitop3:0xf6
	s_lshl_b32 s2, s13, 11
	v_bitop3_b32 v200, s2, v3, v1 bitop3:0xf6
	v_or_b32_e32 v3, s12, v4
	s_lshl_b32 s2, s13, 5
	s_waitcnt vmcnt(4)
	v_or_b32_e32 v201, 0x2000, v3
	v_lshl_or_b32 v3, s14, 11, v4
	s_add_i32 s43, s12, 0
	v_lshl_or_b32 v2, v2, 3, s2
	v_mov_b32_e32 v50, 0
	s_mov_b32 s70, 0
	s_add_i32 s44, s43, 0xe000
	s_add_i32 s45, s43, 0x10000
	s_add_i32 s46, s43, 0x12000
	s_add_i32 s47, s43, 0x14000
	s_add_i32 s48, s43, 0x16000
	s_add_i32 s49, s43, 0x2000
	s_add_i32 s50, s43, 0x6000
	s_add_i32 s51, s43, 0x18000
	s_add_i32 s52, s43, 0x1a000
	s_add_i32 s53, s43, 0x1c000
	s_add_i32 s54, s43, 0x1e000
	s_add_i32 s55, s43, 0xa000
	v_lshl_or_b32 v202, s14, 6, v199
	s_add_i32 s56, s43, 0xd000
	s_add_i32 s57, s43, 0x11000
	s_add_i32 s58, s43, 0x15000
	s_add_i32 s59, s43, 0x1000
	s_add_i32 s60, s43, 0x5000
	s_add_i32 s61, s43, 0x19000
	s_add_i32 s62, s43, 0x1d000
	s_add_i32 s63, s43, 0x9000
	v_or_b32_e32 v203, 0x1400, v2
	v_mov_b64_e32 v[186:187], 0xa20
	v_mov_b64_e32 v[188:189], 0xa1f
	s_add_i32 s64, s43, 0xc000
	v_mov_b32_e32 v204, 0x7f7f7f7f
	s_add_i32 s65, s43, 0x4000
	s_add_i32 s66, s43, 0x8000
	s_mov_b32 s24, 0x3b800000
	s_mov_b32 s67, 0xcc00
	v_add_u32_e32 v205, 0, v5
	v_add_u32_e32 v206, 0, v3
	v_mov_b32_e32 v51, v50
	v_mov_b32_e32 v52, v50
	v_mov_b32_e32 v53, v50
	v_mov_b32_e32 v54, v50
	v_mov_b32_e32 v55, v50
	v_mov_b32_e32 v56, v50
	v_mov_b32_e32 v57, v50
	v_mov_b32_e32 v58, v50
	v_mov_b32_e32 v59, v50
	v_mov_b32_e32 v60, v50
	v_mov_b32_e32 v61, v50
	v_mov_b32_e32 v62, v50
	v_mov_b32_e32 v63, v50
	v_mov_b32_e32 v64, v50
	v_mov_b32_e32 v65, v50
	v_mov_b32_e32 v66, v50
	v_mov_b32_e32 v67, v50
	v_mov_b32_e32 v68, v50
	v_mov_b32_e32 v69, v50
	v_mov_b32_e32 v70, v50
	v_mov_b32_e32 v71, v50
	v_mov_b32_e32 v72, v50
	v_mov_b32_e32 v73, v50
	v_mov_b32_e32 v74, v50
	v_mov_b32_e32 v75, v50
	v_mov_b32_e32 v76, v50
	v_mov_b32_e32 v77, v50
	v_mov_b32_e32 v78, v50
	v_mov_b32_e32 v79, v50
	v_mov_b32_e32 v80, v50
	v_mov_b32_e32 v81, v50
	v_mov_b32_e32 v82, v50
	v_mov_b32_e32 v83, v50
	v_mov_b32_e32 v84, v50
	v_mov_b32_e32 v85, v50
	v_mov_b32_e32 v86, v50
	v_mov_b32_e32 v87, v50
	v_mov_b32_e32 v88, v50
	v_mov_b32_e32 v89, v50
	v_mov_b32_e32 v90, v50
	v_mov_b32_e32 v91, v50
	v_mov_b32_e32 v92, v50
	v_mov_b32_e32 v93, v50
	v_mov_b32_e32 v94, v50
	v_mov_b32_e32 v95, v50
	v_mov_b32_e32 v96, v50
	v_mov_b32_e32 v97, v50
	v_mov_b32_e32 v98, v50
	v_mov_b32_e32 v99, v50
	v_mov_b32_e32 v100, v50
	v_mov_b32_e32 v101, v50
	v_mov_b32_e32 v102, v50
	v_mov_b32_e32 v103, v50
	v_mov_b32_e32 v104, v50
	v_mov_b32_e32 v105, v50
	v_mov_b32_e32 v106, v50
	v_mov_b32_e32 v107, v50
	v_mov_b32_e32 v108, v50
	v_mov_b32_e32 v109, v50
	v_mov_b32_e32 v110, v50
	v_mov_b32_e32 v111, v50
	v_mov_b32_e32 v112, v50
	v_mov_b32_e32 v113, v50
	v_mov_b32_e32 v114, v50
	v_mov_b32_e32 v115, v50
	v_mov_b32_e32 v116, v50
	v_mov_b32_e32 v117, v50
	v_mov_b32_e32 v118, v50
	v_mov_b32_e32 v119, v50
	v_mov_b32_e32 v120, v50
	v_mov_b32_e32 v121, v50
	v_mov_b32_e32 v122, v50
	v_mov_b32_e32 v123, v50
	v_mov_b32_e32 v124, v50
	v_mov_b32_e32 v125, v50
	v_mov_b32_e32 v126, v50
	v_mov_b32_e32 v127, v50
	v_mov_b32_e32 v128, v50
	v_mov_b32_e32 v129, v50
	v_mov_b32_e32 v130, v50
	v_mov_b32_e32 v131, v50
	v_mov_b32_e32 v132, v50
	v_mov_b32_e32 v133, v50
	v_mov_b32_e32 v134, v50
	v_mov_b32_e32 v135, v50
	v_mov_b32_e32 v136, v50
	v_mov_b32_e32 v137, v50
	v_mov_b32_e32 v138, v50
	v_mov_b32_e32 v139, v50
	v_mov_b32_e32 v140, v50
	v_mov_b32_e32 v141, v50
	v_mov_b32_e32 v142, v50
	v_mov_b32_e32 v143, v50
	v_mov_b32_e32 v144, v50
	v_mov_b32_e32 v145, v50
	v_mov_b32_e32 v146, v50
	v_mov_b32_e32 v147, v50
	v_mov_b32_e32 v148, v50
	v_mov_b32_e32 v149, v50
	v_mov_b32_e32 v150, v50
	v_mov_b32_e32 v151, v50
	v_mov_b32_e32 v152, v50
	v_mov_b32_e32 v153, v50
	v_mov_b32_e32 v154, v50
	v_mov_b32_e32 v155, v50
	v_mov_b32_e32 v156, v50
	v_mov_b32_e32 v157, v50
	v_mov_b32_e32 v158, v50
	v_mov_b32_e32 v159, v50
	v_mov_b32_e32 v160, v50
	v_mov_b32_e32 v161, v50
	v_mov_b32_e32 v162, v50
	v_mov_b32_e32 v163, v50
	v_mov_b32_e32 v164, v50
	v_mov_b32_e32 v165, v50
	v_mov_b32_e32 v166, v50
	v_mov_b32_e32 v167, v50
	v_mov_b32_e32 v168, v50
	v_mov_b32_e32 v169, v50
	v_mov_b32_e32 v170, v50
	v_mov_b32_e32 v171, v50
	v_mov_b32_e32 v172, v50
	v_mov_b32_e32 v173, v50
	v_mov_b32_e32 v174, v50
	v_mov_b32_e32 v175, v50
	v_mov_b32_e32 v176, v50
	v_mov_b32_e32 v177, v50
	s_barrier
	s_mov_b32 s32, 1
	v_mov_b32_e32 v244, v180
	v_mov_b32_e32 v245, v182
	v_mov_b32_e32 v246, v184
	s_branch .LBB0_968

.LBB0_976:
	v_add_u32_e32 v247, 0x10000, v200
	v_add_u32_e32 v248, 0x10000, v201
	s_and_b64 vcc, exec, s[4:5]
	s_cbranch_vccz .Lsp1_in_L1

.Lsp0_rd_L1:
	ds_read_b128 v[44:47], v205
	ds_read_b64 v[48:49], v206 offset:8192
	ds_read_b128 v[38:41], v205 offset:1024
	ds_read_b64 v[42:43], v206 offset:8704
	ds_read_b128 v[32:35], v205 offset:2048
	ds_read_b64 v[36:37], v206 offset:9216
	ds_read_b128 v[26:29], v205 offset:3072
	ds_read_b64 v[30:31], v206 offset:9728
	ds_read_b128 v[20:23], v247
	ds_read_b64 v[24:25], v248
	ds_read_b128 v[14:17], v247 offset:1024
	ds_read_b64 v[18:19], v248 offset:512
	ds_read_b128 v[8:11], v247 offset:16384
	ds_read_b64 v[12:13], v248 offset:16384
	ds_read_b128 v[2:5], v247 offset:17408
	ds_read_b64 v[6:7], v248 offset:16896
	s_waitcnt lgkmcnt(0)
	s_barrier
.Lsp0_top_L1:
	s_add_u32 s34, s2, 0xfffa3000
	s_addc_u32 s35, s3, -1
	s_cmp_eq_u32 s73, 28
	s_cselect_b32 s28, s26, s33
	s_cselect_b32 s29, s27, s72
	s_cselect_b32 s30, s14, s34
	s_cselect_b32 s31, s15, s35
	s_add_u32 s34, s28, 0x60000
	s_addc_u32 s35, s29, 0
	s_mov_b32 m0, s49
	v_mfma_scale_f32_16x16x128_f8f6f4 v[174:177], v[20:25], v[44:49], v[174:177], v204, v204 op_sel_hi:[0,0,0] cbsz:2 blgp:2
	global_load_lds_dwordx4 v246, s[30:31]
	v_mfma_scale_f32_16x16x128_f8f6f4 v[170:173], v[14:19], v[44:49], v[170:173], v204, v204 op_sel_hi:[0,0,0] cbsz:2 blgp:2
	ds_read_b128 v[208:211], v205 offset:16384
	v_mfma_scale_f32_16x16x128_f8f6f4 v[166:169], v[20:25], v[38:43], v[166:169], v204, v204 op_sel_hi:[0,0,0] cbsz:2 blgp:2
	ds_read_b64 v[212:213], v206 offset:24576
	s_mov_b32 m0, s46
	v_mfma_scale_f32_16x16x128_f8f6f4 v[162:165], v[14:19], v[38:43], v[162:165], v204, v204 op_sel_hi:[0,0,0] cbsz:2 blgp:2
	global_load_lds_dwordx4 v246, s[28:29]
	v_mfma_scale_f32_16x16x128_f8f6f4 v[158:161], v[20:25], v[32:37], v[158:161], v204, v204 op_sel_hi:[0,0,0] cbsz:2 blgp:2
	ds_read_b128 v[214:217], v205 offset:17408
	v_mfma_scale_f32_16x16x128_f8f6f4 v[154:157], v[14:19], v[32:37], v[154:157], v204, v204 op_sel_hi:[0,0,0] cbsz:2 blgp:2
	ds_read_b64 v[218:219], v206 offset:25088
	s_mov_b32 m0, s47
	v_mfma_scale_f32_16x16x128_f8f6f4 v[150:153], v[20:25], v[26:31], v[150:153], v204, v204 op_sel_hi:[0,0,0] cbsz:2 blgp:2
	global_load_lds_dwordx4 v244, s[34:35]
	v_mfma_scale_f32_16x16x128_f8f6f4 v[146:149], v[14:19], v[26:31], v[146:149], v204, v204 op_sel_hi:[0,0,0] cbsz:2 blgp:2
	ds_read_b128 v[220:223], v205 offset:18432
	v_mfma_scale_f32_16x16x128_f8f6f4 v[142:145], v[8:13], v[44:49], v[142:145], v204, v204 op_sel_hi:[0,0,0] cbsz:2 blgp:2
	ds_read_b64 v[224:225], v206 offset:25600
	s_mov_b32 m0, s58
	v_mfma_scale_f32_16x16x128_f8f6f4 v[138:141], v[2:7], v[44:49], v[138:141], v204, v204 op_sel_hi:[0,0,0] cbsz:2 blgp:2
	global_load_lds_dwordx4 v245, s[34:35]
	v_mfma_scale_f32_16x16x128_f8f6f4 v[134:137], v[8:13], v[38:43], v[134:137], v204, v204 op_sel_hi:[0,0,0] cbsz:2 blgp:2
	ds_read_b128 v[226:229], v205 offset:19456
	v_mfma_scale_f32_16x16x128_f8f6f4 v[130:133], v[2:7], v[38:43], v[130:133], v204, v204 op_sel_hi:[0,0,0] cbsz:2 blgp:2
	ds_read_b64 v[230:231], v206 offset:26112
	v_mfma_scale_f32_16x16x128_f8f6f4 v[126:129], v[8:13], v[32:37], v[126:129], v204, v204 op_sel_hi:[0,0,0] cbsz:2 blgp:2
	v_mfma_scale_f32_16x16x128_f8f6f4 v[122:125], v[2:7], v[32:37], v[122:125], v204, v204 op_sel_hi:[0,0,0] cbsz:2 blgp:2
	v_mfma_scale_f32_16x16x128_f8f6f4 v[118:121], v[8:13], v[26:31], v[118:121], v204, v204 op_sel_hi:[0,0,0] cbsz:2 blgp:2
	v_mfma_scale_f32_16x16x128_f8f6f4 v[114:117], v[2:7], v[26:31], v[114:117], v204, v204 op_sel_hi:[0,0,0] cbsz:2 blgp:2
	s_waitcnt vmcnt(6)
	s_waitcnt lgkmcnt(0)
	s_barrier
	s_add_u32 s34, s30, 0x60000
	s_addc_u32 s35, s31, 0
	s_mov_b32 m0, s65
	v_mfma_scale_f32_16x16x128_f8f6f4 v[110:113], v[20:25], v[208:213], v[110:113], v204, v204 op_sel_hi:[0,0,0] cbsz:2 blgp:2
	global_load_lds_dwordx4 v244, s[34:35]
	ds_read_b128 v[44:47], v205 offset:32768
	s_mov_b32 m0, s60
	v_mfma_scale_f32_16x16x128_f8f6f4 v[106:109], v[14:19], v[208:213], v[106:109], v204, v204 op_sel_hi:[0,0,0] cbsz:2 blgp:2
	ds_read_b64 v[48:49], v206 offset:40960
	global_load_lds_dwordx4 v245, s[34:35]
	v_mfma_scale_f32_16x16x128_f8f6f4 v[102:105], v[20:25], v[214:219], v[102:105], v204, v204 op_sel_hi:[0,0,0] cbsz:2 blgp:2
	ds_read_b128 v[38:41], v205 offset:33792
	ds_read_b64 v[42:43], v206 offset:41472
	v_mfma_scale_f32_16x16x128_f8f6f4 v[98:101], v[14:19], v[214:219], v[98:101], v204, v204 op_sel_hi:[0,0,0] cbsz:2 blgp:2
	ds_read_b128 v[32:35], v205 offset:34816
	ds_read_b64 v[36:37], v206 offset:41984
	v_mfma_scale_f32_16x16x128_f8f6f4 v[94:97], v[20:25], v[220:225], v[94:97], v204, v204 op_sel_hi:[0,0,0] cbsz:2 blgp:2
	ds_read_b128 v[26:29], v205 offset:35840
	ds_read_b64 v[30:31], v206 offset:42496
	v_mfma_scale_f32_16x16x128_f8f6f4 v[90:93], v[14:19], v[220:225], v[90:93], v204, v204 op_sel_hi:[0,0,0] cbsz:2 blgp:2
	ds_read_b128 v[232:235], v247 offset:32768
	ds_read_b64 v[236:237], v248 offset:32768
	v_mfma_scale_f32_16x16x128_f8f6f4 v[86:89], v[20:25], v[226:231], v[86:89], v204, v204 op_sel_hi:[0,0,0] cbsz:2 blgp:2
	ds_read_b128 v[238:241], v247 offset:33792
	ds_read_b64 v[242:243], v248 offset:33280
	v_mfma_scale_f32_16x16x128_f8f6f4 v[82:85], v[14:19], v[226:231], v[82:85], v204, v204 op_sel_hi:[0,0,0] cbsz:2 blgp:2
	ds_read_b128 v[180:183], v247 offset:49152
	ds_read_b64 v[184:185], v248 offset:49152
	v_mfma_scale_f32_16x16x128_f8f6f4 v[78:81], v[8:13], v[208:213], v[78:81], v204, v204 op_sel_hi:[0,0,0] cbsz:2 blgp:2
	ds_read_b128 v[250:253], v247 offset:50176
	ds_read_b64 v[254:255], v248 offset:49664
	v_mfma_scale_f32_16x16x128_f8f6f4 v[74:77], v[2:7], v[208:213], v[74:77], v204, v204 op_sel_hi:[0,0,0] cbsz:2 blgp:2
	v_mfma_scale_f32_16x16x128_f8f6f4 v[70:73], v[8:13], v[214:219], v[70:73], v204, v204 op_sel_hi:[0,0,0] cbsz:2 blgp:2
	v_mfma_scale_f32_16x16x128_f8f6f4 v[66:69], v[2:7], v[214:219], v[66:69], v204, v204 op_sel_hi:[0,0,0] cbsz:2 blgp:2
	v_mfma_scale_f32_16x16x128_f8f6f4 v[62:65], v[8:13], v[220:225], v[62:65], v204, v204 op_sel_hi:[0,0,0] cbsz:2 blgp:2
	v_mfma_scale_f32_16x16x128_f8f6f4 v[58:61], v[2:7], v[220:225], v[58:61], v204, v204 op_sel_hi:[0,0,0] cbsz:2 blgp:2
	v_mfma_scale_f32_16x16x128_f8f6f4 v[54:57], v[8:13], v[226:231], v[54:57], v204, v204 op_sel_hi:[0,0,0] cbsz:2 blgp:2
	v_mfma_scale_f32_16x16x128_f8f6f4 v[50:53], v[2:7], v[226:231], v[50:53], v204, v204 op_sel_hi:[0,0,0] cbsz:2 blgp:2
	s_waitcnt vmcnt(6)
	s_waitcnt lgkmcnt(0)
	s_barrier
	s_add_u32 s30, s30, 0x3000
	s_addc_u32 s31, s31, 0
	s_add_u32 s28, s28, 0x3000
	s_addc_u32 s29, s29, 0
	s_add_u32 s34, s28, 0x60000
	s_addc_u32 s35, s29, 0
	s_mov_b32 m0, s55
	v_mfma_scale_f32_16x16x128_f8f6f4 v[174:177], v[232:237], v[44:49], v[174:177], v204, v204 op_sel_hi:[0,0,0] cbsz:2 blgp:2
	global_load_lds_dwordx4 v246, s[30:31]
	v_mfma_scale_f32_16x16x128_f8f6f4 v[170:173], v[238:243], v[44:49], v[170:173], v204, v204 op_sel_hi:[0,0,0] cbsz:2 blgp:2
	ds_read_b128 v[208:211], v205 offset:49152
	v_mfma_scale_f32_16x16x128_f8f6f4 v[166:169], v[232:237], v[38:43], v[166:169], v204, v204 op_sel_hi:[0,0,0] cbsz:2 blgp:2
	ds_read_b64 v[212:213], v206 offset:57344
	s_mov_b32 m0, s52
	v_mfma_scale_f32_16x16x128_f8f6f4 v[162:165], v[238:243], v[38:43], v[162:165], v204, v204 op_sel_hi:[0,0,0] cbsz:2 blgp:2
	global_load_lds_dwordx4 v246, s[28:29]
	v_mfma_scale_f32_16x16x128_f8f6f4 v[158:161], v[232:237], v[32:37], v[158:161], v204, v204 op_sel_hi:[0,0,0] cbsz:2 blgp:2
	ds_read_b128 v[214:217], v205 offset:50176
	v_mfma_scale_f32_16x16x128_f8f6f4 v[154:157], v[238:243], v[32:37], v[154:157], v204, v204 op_sel_hi:[0,0,0] cbsz:2 blgp:2
	ds_read_b64 v[218:219], v206 offset:57856
	s_mov_b32 m0, s53
	v_mfma_scale_f32_16x16x128_f8f6f4 v[150:153], v[232:237], v[26:31], v[150:153], v204, v204 op_sel_hi:[0,0,0] cbsz:2 blgp:2
	global_load_lds_dwordx4 v244, s[34:35]
	v_mfma_scale_f32_16x16x128_f8f6f4 v[146:149], v[238:243], v[26:31], v[146:149], v204, v204 op_sel_hi:[0,0,0] cbsz:2 blgp:2
	ds_read_b128 v[220:223], v205 offset:51200
	v_mfma_scale_f32_16x16x128_f8f6f4 v[142:145], v[180:185], v[44:49], v[142:145], v204, v204 op_sel_hi:[0,0,0] cbsz:2 blgp:2
	ds_read_b64 v[224:225], v206 offset:58368
	s_mov_b32 m0, s62
	v_mfma_scale_f32_16x16x128_f8f6f4 v[138:141], v[250:255], v[44:49], v[138:141], v204, v204 op_sel_hi:[0,0,0] cbsz:2 blgp:2
	global_load_lds_dwordx4 v245, s[34:35]
	v_mfma_scale_f32_16x16x128_f8f6f4 v[134:137], v[180:185], v[38:43], v[134:137], v204, v204 op_sel_hi:[0,0,0] cbsz:2 blgp:2
	ds_read_b128 v[226:229], v205 offset:52224
	v_mfma_scale_f32_16x16x128_f8f6f4 v[130:133], v[250:255], v[38:43], v[130:133], v204, v204 op_sel_hi:[0,0,0] cbsz:2 blgp:2
	ds_read_b64 v[230:231], v206 offset:58880
	v_mfma_scale_f32_16x16x128_f8f6f4 v[126:129], v[180:185], v[32:37], v[126:129], v204, v204 op_sel_hi:[0,0,0] cbsz:2 blgp:2
	v_mfma_scale_f32_16x16x128_f8f6f4 v[122:125], v[250:255], v[32:37], v[122:125], v204, v204 op_sel_hi:[0,0,0] cbsz:2 blgp:2
	v_mfma_scale_f32_16x16x128_f8f6f4 v[118:121], v[180:185], v[26:31], v[118:121], v204, v204 op_sel_hi:[0,0,0] cbsz:2 blgp:2
	v_mfma_scale_f32_16x16x128_f8f6f4 v[114:117], v[250:255], v[26:31], v[114:117], v204, v204 op_sel_hi:[0,0,0] cbsz:2 blgp:2
	s_waitcnt vmcnt(6)
	s_waitcnt lgkmcnt(0)
	s_barrier
	s_add_u32 s34, s30, 0x60000
	s_addc_u32 s35, s31, 0
	s_mov_b32 m0, s64
	v_mfma_scale_f32_16x16x128_f8f6f4 v[110:113], v[232:237], v[208:213], v[110:113], v204, v204 op_sel_hi:[0,0,0] cbsz:2 blgp:2
	global_load_lds_dwordx4 v244, s[34:35]
	ds_read_b128 v[44:47], v205
	s_mov_b32 m0, s56
	v_mfma_scale_f32_16x16x128_f8f6f4 v[106:109], v[238:243], v[208:213], v[106:109], v204, v204 op_sel_hi:[0,0,0] cbsz:2 blgp:2
	ds_read_b64 v[48:49], v206 offset:8192
	global_load_lds_dwordx4 v245, s[34:35]
	v_mfma_scale_f32_16x16x128_f8f6f4 v[102:105], v[232:237], v[214:219], v[102:105], v204, v204 op_sel_hi:[0,0,0] cbsz:2 blgp:2
	ds_read_b128 v[38:41], v205 offset:1024
	ds_read_b64 v[42:43], v206 offset:8704
	v_mfma_scale_f32_16x16x128_f8f6f4 v[98:101], v[238:243], v[214:219], v[98:101], v204, v204 op_sel_hi:[0,0,0] cbsz:2 blgp:2
	ds_read_b128 v[32:35], v205 offset:2048
	ds_read_b64 v[36:37], v206 offset:9216
	v_mfma_scale_f32_16x16x128_f8f6f4 v[94:97], v[232:237], v[220:225], v[94:97], v204, v204 op_sel_hi:[0,0,0] cbsz:2 blgp:2
	ds_read_b128 v[26:29], v205 offset:3072
	ds_read_b64 v[30:31], v206 offset:9728
	v_mfma_scale_f32_16x16x128_f8f6f4 v[90:93], v[238:243], v[220:225], v[90:93], v204, v204 op_sel_hi:[0,0,0] cbsz:2 blgp:2
	ds_read_b128 v[20:23], v247
	ds_read_b64 v[24:25], v248
	v_mfma_scale_f32_16x16x128_f8f6f4 v[86:89], v[232:237], v[226:231], v[86:89], v204, v204 op_sel_hi:[0,0,0] cbsz:2 blgp:2
	ds_read_b128 v[14:17], v247 offset:1024
	ds_read_b64 v[18:19], v248 offset:512
	v_mfma_scale_f32_16x16x128_f8f6f4 v[82:85], v[238:243], v[226:231], v[82:85], v204, v204 op_sel_hi:[0,0,0] cbsz:2 blgp:2
	ds_read_b128 v[8:11], v247 offset:16384
	ds_read_b64 v[12:13], v248 offset:16384
	v_mfma_scale_f32_16x16x128_f8f6f4 v[78:81], v[180:185], v[208:213], v[78:81], v204, v204 op_sel_hi:[0,0,0] cbsz:2 blgp:2
	ds_read_b128 v[2:5], v247 offset:17408
	ds_read_b64 v[6:7], v248 offset:16896
	v_mfma_scale_f32_16x16x128_f8f6f4 v[74:77], v[250:255], v[208:213], v[74:77], v204, v204 op_sel_hi:[0,0,0] cbsz:2 blgp:2
	v_mfma_scale_f32_16x16x128_f8f6f4 v[70:73], v[180:185], v[214:219], v[70:73], v204, v204 op_sel_hi:[0,0,0] cbsz:2 blgp:2
	v_mfma_scale_f32_16x16x128_f8f6f4 v[66:69], v[250:255], v[214:219], v[66:69], v204, v204 op_sel_hi:[0,0,0] cbsz:2 blgp:2
	v_mfma_scale_f32_16x16x128_f8f6f4 v[62:65], v[180:185], v[220:225], v[62:65], v204, v204 op_sel_hi:[0,0,0] cbsz:2 blgp:2
	v_mfma_scale_f32_16x16x128_f8f6f4 v[58:61], v[250:255], v[220:225], v[58:61], v204, v204 op_sel_hi:[0,0,0] cbsz:2 blgp:2
	v_mfma_scale_f32_16x16x128_f8f6f4 v[54:57], v[180:185], v[226:231], v[54:57], v204, v204 op_sel_hi:[0,0,0] cbsz:2 blgp:2
	v_mfma_scale_f32_16x16x128_f8f6f4 v[50:53], v[250:255], v[226:231], v[50:53], v204, v204 op_sel_hi:[0,0,0] cbsz:2 blgp:2
	s_waitcnt vmcnt(6)
	s_waitcnt lgkmcnt(0)
	s_barrier
	s_add_i32 s73, s73, 2
	s_add_u32 s2, s2, 0x6000
	s_addc_u32 s3, s3, 0
	s_add_u32 s33, s33, 0x6000
	s_addc_u32 s72, s72, 0
	s_cmp_gt_u32 s73, 29
	s_cbranch_scc0 .Lsp0_top_L1
	s_branch .LBB0_992

.Lsp1_top_L1:
	s_add_u32 s34, s2, 0xfffa3000
	s_addc_u32 s35, s3, -1
	s_cmp_eq_u32 s73, 28
	s_cselect_b32 s28, s26, s33
	s_cselect_b32 s29, s27, s72
	s_cselect_b32 s30, s14, s34
	s_cselect_b32 s31, s15, s35
	s_add_u32 s34, s28, 0x60000
	s_addc_u32 s35, s29, 0
	s_mov_b32 m0, s43
	v_mfma_scale_f32_16x16x128_f8f6f4 v[174:177], v[20:25], v[44:49], v[174:177], v204, v204 op_sel_hi:[0,0,0] cbsz:2 blgp:2
	global_load_lds_dwordx4 v244, s[30:31]
	v_mfma_scale_f32_16x16x128_f8f6f4 v[170:173], v[14:19], v[44:49], v[170:173], v204, v204 op_sel_hi:[0,0,0] cbsz:2 blgp:2
	ds_read_b128 v[208:211], v205 offset:16384
	v_mfma_scale_f32_16x16x128_f8f6f4 v[166:169], v[20:25], v[38:43], v[166:169], v204, v204 op_sel_hi:[0,0,0] cbsz:2 blgp:2
	ds_read_b64 v[212:213], v206 offset:24576
	s_mov_b32 m0, s59
	v_mfma_scale_f32_16x16x128_f8f6f4 v[162:165], v[14:19], v[38:43], v[162:165], v204, v204 op_sel_hi:[0,0,0] cbsz:2 blgp:2
	global_load_lds_dwordx4 v245, s[30:31]
	v_mfma_scale_f32_16x16x128_f8f6f4 v[158:161], v[20:25], v[32:37], v[158:161], v204, v204 op_sel_hi:[0,0,0] cbsz:2 blgp:2
	ds_read_b128 v[214:217], v205 offset:17408
	v_mfma_scale_f32_16x16x128_f8f6f4 v[154:157], v[14:19], v[32:37], v[154:157], v204, v204 op_sel_hi:[0,0,0] cbsz:2 blgp:2
	ds_read_b64 v[218:219], v206 offset:25088
	s_mov_b32 m0, s45
	v_mfma_scale_f32_16x16x128_f8f6f4 v[150:153], v[20:25], v[26:31], v[150:153], v204, v204 op_sel_hi:[0,0,0] cbsz:2 blgp:2
	global_load_lds_dwordx4 v244, s[28:29]
	v_mfma_scale_f32_16x16x128_f8f6f4 v[146:149], v[14:19], v[26:31], v[146:149], v204, v204 op_sel_hi:[0,0,0] cbsz:2 blgp:2
	ds_read_b128 v[220:223], v205 offset:18432
	v_mfma_scale_f32_16x16x128_f8f6f4 v[142:145], v[8:13], v[44:49], v[142:145], v204, v204 op_sel_hi:[0,0,0] cbsz:2 blgp:2
	ds_read_b64 v[224:225], v206 offset:25600
	s_mov_b32 m0, s57
	v_mfma_scale_f32_16x16x128_f8f6f4 v[138:141], v[2:7], v[44:49], v[138:141], v204, v204 op_sel_hi:[0,0,0] cbsz:2 blgp:2
	global_load_lds_dwordx4 v245, s[28:29]
	v_mfma_scale_f32_16x16x128_f8f6f4 v[134:137], v[8:13], v[38:43], v[134:137], v204, v204 op_sel_hi:[0,0,0] cbsz:2 blgp:2
	ds_read_b128 v[226:229], v205 offset:19456
	v_mfma_scale_f32_16x16x128_f8f6f4 v[130:133], v[2:7], v[38:43], v[130:133], v204, v204 op_sel_hi:[0,0,0] cbsz:2 blgp:2
	ds_read_b64 v[230:231], v206 offset:26112
	s_mov_b32 m0, s48
	v_mfma_scale_f32_16x16x128_f8f6f4 v[126:129], v[8:13], v[32:37], v[126:129], v204, v204 op_sel_hi:[0,0,0] cbsz:2 blgp:2
	global_load_lds_dwordx4 v246, s[34:35]
	v_mfma_scale_f32_16x16x128_f8f6f4 v[122:125], v[2:7], v[32:37], v[122:125], v204, v204 op_sel_hi:[0,0,0] cbsz:2 blgp:2
	v_mfma_scale_f32_16x16x128_f8f6f4 v[118:121], v[8:13], v[26:31], v[118:121], v204, v204 op_sel_hi:[0,0,0] cbsz:2 blgp:2
	v_mfma_scale_f32_16x16x128_f8f6f4 v[114:117], v[2:7], v[26:31], v[114:117], v204, v204 op_sel_hi:[0,0,0] cbsz:2 blgp:2
	s_waitcnt vmcnt(6)
	s_waitcnt lgkmcnt(0)
	s_barrier
	s_add_u32 s34, s30, 0x60000
	s_addc_u32 s35, s31, 0
	s_mov_b32 m0, s50
	v_mfma_scale_f32_16x16x128_f8f6f4 v[110:113], v[20:25], v[208:213], v[110:113], v204, v204 op_sel_hi:[0,0,0] cbsz:2 blgp:2
	global_load_lds_dwordx4 v246, s[34:35]
	ds_read_b128 v[44:47], v205 offset:32768
	v_mfma_scale_f32_16x16x128_f8f6f4 v[106:109], v[14:19], v[208:213], v[106:109], v204, v204 op_sel_hi:[0,0,0] cbsz:2 blgp:2
	ds_read_b64 v[48:49], v206 offset:40960
	ds_read_b128 v[38:41], v205 offset:33792
	v_mfma_scale_f32_16x16x128_f8f6f4 v[102:105], v[20:25], v[214:219], v[102:105], v204, v204 op_sel_hi:[0,0,0] cbsz:2 blgp:2
	ds_read_b64 v[42:43], v206 offset:41472
	ds_read_b128 v[32:35], v205 offset:34816
	v_mfma_scale_f32_16x16x128_f8f6f4 v[98:101], v[14:19], v[214:219], v[98:101], v204, v204 op_sel_hi:[0,0,0] cbsz:2 blgp:2
	ds_read_b64 v[36:37], v206 offset:41984
	ds_read_b128 v[26:29], v205 offset:35840
	v_mfma_scale_f32_16x16x128_f8f6f4 v[94:97], v[20:25], v[220:225], v[94:97], v204, v204 op_sel_hi:[0,0,0] cbsz:2 blgp:2
	ds_read_b64 v[30:31], v206 offset:42496
	ds_read_b128 v[232:235], v247 offset:32768
	v_mfma_scale_f32_16x16x128_f8f6f4 v[90:93], v[14:19], v[220:225], v[90:93], v204, v204 op_sel_hi:[0,0,0] cbsz:2 blgp:2
	ds_read_b64 v[236:237], v248 offset:32768
	ds_read_b128 v[238:241], v247 offset:33792
	v_mfma_scale_f32_16x16x128_f8f6f4 v[86:89], v[20:25], v[226:231], v[86:89], v204, v204 op_sel_hi:[0,0,0] cbsz:2 blgp:2
	ds_read_b64 v[242:243], v248 offset:33280
	ds_read_b128 v[180:183], v247 offset:49152
	v_mfma_scale_f32_16x16x128_f8f6f4 v[82:85], v[14:19], v[226:231], v[82:85], v204, v204 op_sel_hi:[0,0,0] cbsz:2 blgp:2
	ds_read_b64 v[184:185], v248 offset:49152
	ds_read_b128 v[250:253], v247 offset:50176
	v_mfma_scale_f32_16x16x128_f8f6f4 v[78:81], v[8:13], v[208:213], v[78:81], v204, v204 op_sel_hi:[0,0,0] cbsz:2 blgp:2
	ds_read_b64 v[254:255], v248 offset:49664
	v_mfma_scale_f32_16x16x128_f8f6f4 v[74:77], v[2:7], v[208:213], v[74:77], v204, v204 op_sel_hi:[0,0,0] cbsz:2 blgp:2
	v_mfma_scale_f32_16x16x128_f8f6f4 v[70:73], v[8:13], v[214:219], v[70:73], v204, v204 op_sel_hi:[0,0,0] cbsz:2 blgp:2
	v_mfma_scale_f32_16x16x128_f8f6f4 v[66:69], v[2:7], v[214:219], v[66:69], v204, v204 op_sel_hi:[0,0,0] cbsz:2 blgp:2
	v_mfma_scale_f32_16x16x128_f8f6f4 v[62:65], v[8:13], v[220:225], v[62:65], v204, v204 op_sel_hi:[0,0,0] cbsz:2 blgp:2
	v_mfma_scale_f32_16x16x128_f8f6f4 v[58:61], v[2:7], v[220:225], v[58:61], v204, v204 op_sel_hi:[0,0,0] cbsz:2 blgp:2
	v_mfma_scale_f32_16x16x128_f8f6f4 v[54:57], v[8:13], v[226:231], v[54:57], v204, v204 op_sel_hi:[0,0,0] cbsz:2 blgp:2
	v_mfma_scale_f32_16x16x128_f8f6f4 v[50:53], v[2:7], v[226:231], v[50:53], v204, v204 op_sel_hi:[0,0,0] cbsz:2 blgp:2
	s_waitcnt vmcnt(6)
	s_waitcnt lgkmcnt(0)
	s_barrier
	s_add_u32 s30, s30, 0x3000
	s_addc_u32 s31, s31, 0
	s_add_u32 s28, s28, 0x3000
	s_addc_u32 s29, s29, 0
	s_add_u32 s34, s28, 0x60000
	s_addc_u32 s35, s29, 0
	s_mov_b32 m0, s66
	v_mfma_scale_f32_16x16x128_f8f6f4 v[174:177], v[232:237], v[44:49], v[174:177], v204, v204 op_sel_hi:[0,0,0] cbsz:2 blgp:2
	global_load_lds_dwordx4 v244, s[30:31]
	v_mfma_scale_f32_16x16x128_f8f6f4 v[170:173], v[238:243], v[44:49], v[170:173], v204, v204 op_sel_hi:[0,0,0] cbsz:2 blgp:2
	ds_read_b128 v[208:211], v205 offset:49152
	v_mfma_scale_f32_16x16x128_f8f6f4 v[166:169], v[232:237], v[38:43], v[166:169], v204, v204 op_sel_hi:[0,0,0] cbsz:2 blgp:2
	ds_read_b64 v[212:213], v206 offset:57344
	s_mov_b32 m0, s63
	v_mfma_scale_f32_16x16x128_f8f6f4 v[162:165], v[238:243], v[38:43], v[162:165], v204, v204 op_sel_hi:[0,0,0] cbsz:2 blgp:2
	global_load_lds_dwordx4 v245, s[30:31]
	v_mfma_scale_f32_16x16x128_f8f6f4 v[158:161], v[232:237], v[32:37], v[158:161], v204, v204 op_sel_hi:[0,0,0] cbsz:2 blgp:2
	ds_read_b128 v[214:217], v205 offset:50176
	v_mfma_scale_f32_16x16x128_f8f6f4 v[154:157], v[238:243], v[32:37], v[154:157], v204, v204 op_sel_hi:[0,0,0] cbsz:2 blgp:2
	ds_read_b64 v[218:219], v206 offset:57856
	s_mov_b32 m0, s51
	v_mfma_scale_f32_16x16x128_f8f6f4 v[150:153], v[232:237], v[26:31], v[150:153], v204, v204 op_sel_hi:[0,0,0] cbsz:2 blgp:2
	global_load_lds_dwordx4 v244, s[28:29]
	v_mfma_scale_f32_16x16x128_f8f6f4 v[146:149], v[238:243], v[26:31], v[146:149], v204, v204 op_sel_hi:[0,0,0] cbsz:2 blgp:2
	ds_read_b128 v[220:223], v205 offset:51200
	v_mfma_scale_f32_16x16x128_f8f6f4 v[142:145], v[180:185], v[44:49], v[142:145], v204, v204 op_sel_hi:[0,0,0] cbsz:2 blgp:2
	ds_read_b64 v[224:225], v206 offset:58368
	s_mov_b32 m0, s61
	v_mfma_scale_f32_16x16x128_f8f6f4 v[138:141], v[250:255], v[44:49], v[138:141], v204, v204 op_sel_hi:[0,0,0] cbsz:2 blgp:2
	global_load_lds_dwordx4 v245, s[28:29]
	v_mfma_scale_f32_16x16x128_f8f6f4 v[134:137], v[180:185], v[38:43], v[134:137], v204, v204 op_sel_hi:[0,0,0] cbsz:2 blgp:2
	ds_read_b128 v[226:229], v205 offset:52224
	v_mfma_scale_f32_16x16x128_f8f6f4 v[130:133], v[250:255], v[38:43], v[130:133], v204, v204 op_sel_hi:[0,0,0] cbsz:2 blgp:2
	ds_read_b64 v[230:231], v206 offset:58880
	s_mov_b32 m0, s54
	v_mfma_scale_f32_16x16x128_f8f6f4 v[126:129], v[180:185], v[32:37], v[126:129], v204, v204 op_sel_hi:[0,0,0] cbsz:2 blgp:2
	global_load_lds_dwordx4 v246, s[34:35]
	v_mfma_scale_f32_16x16x128_f8f6f4 v[122:125], v[250:255], v[32:37], v[122:125], v204, v204 op_sel_hi:[0,0,0] cbsz:2 blgp:2
	v_mfma_scale_f32_16x16x128_f8f6f4 v[118:121], v[180:185], v[26:31], v[118:121], v204, v204 op_sel_hi:[0,0,0] cbsz:2 blgp:2
	v_mfma_scale_f32_16x16x128_f8f6f4 v[114:117], v[250:255], v[26:31], v[114:117], v204, v204 op_sel_hi:[0,0,0] cbsz:2 blgp:2
	s_waitcnt vmcnt(6)
	s_waitcnt lgkmcnt(0)
	s_barrier
	s_add_u32 s34, s30, 0x60000
	s_addc_u32 s35, s31, 0
	s_mov_b32 m0, s44
	v_mfma_scale_f32_16x16x128_f8f6f4 v[110:113], v[232:237], v[208:213], v[110:113], v204, v204 op_sel_hi:[0,0,0] cbsz:2 blgp:2
	global_load_lds_dwordx4 v246, s[34:35]
	ds_read_b128 v[44:47], v205
	v_mfma_scale_f32_16x16x128_f8f6f4 v[106:109], v[238:243], v[208:213], v[106:109], v204, v204 op_sel_hi:[0,0,0] cbsz:2 blgp:2
	ds_read_b64 v[48:49], v206 offset:8192
	ds_read_b128 v[38:41], v205 offset:1024
	v_mfma_scale_f32_16x16x128_f8f6f4 v[102:105], v[232:237], v[214:219], v[102:105], v204, v204 op_sel_hi:[0,0,0] cbsz:2 blgp:2
	ds_read_b64 v[42:43], v206 offset:8704
	ds_read_b128 v[32:35], v205 offset:2048
	v_mfma_scale_f32_16x16x128_f8f6f4 v[98:101], v[238:243], v[214:219], v[98:101], v204, v204 op_sel_hi:[0,0,0] cbsz:2 blgp:2
	ds_read_b64 v[36:37], v206 offset:9216
	ds_read_b128 v[26:29], v205 offset:3072
	v_mfma_scale_f32_16x16x128_f8f6f4 v[94:97], v[232:237], v[220:225], v[94:97], v204, v204 op_sel_hi:[0,0,0] cbsz:2 blgp:2
	ds_read_b64 v[30:31], v206 offset:9728
	ds_read_b128 v[20:23], v247
	v_mfma_scale_f32_16x16x128_f8f6f4 v[90:93], v[238:243], v[220:225], v[90:93], v204, v204 op_sel_hi:[0,0,0] cbsz:2 blgp:2
	ds_read_b64 v[24:25], v248
	ds_read_b128 v[14:17], v247 offset:1024
	v_mfma_scale_f32_16x16x128_f8f6f4 v[86:89], v[232:237], v[226:231], v[86:89], v204, v204 op_sel_hi:[0,0,0] cbsz:2 blgp:2
	ds_read_b64 v[18:19], v248 offset:512
	ds_read_b128 v[8:11], v247 offset:16384
	v_mfma_scale_f32_16x16x128_f8f6f4 v[82:85], v[238:243], v[226:231], v[82:85], v204, v204 op_sel_hi:[0,0,0] cbsz:2 blgp:2
	ds_read_b64 v[12:13], v248 offset:16384
	ds_read_b128 v[2:5], v247 offset:17408
	v_mfma_scale_f32_16x16x128_f8f6f4 v[78:81], v[180:185], v[208:213], v[78:81], v204, v204 op_sel_hi:[0,0,0] cbsz:2 blgp:2
	ds_read_b64 v[6:7], v248 offset:16896
	v_mfma_scale_f32_16x16x128_f8f6f4 v[74:77], v[250:255], v[208:213], v[74:77], v204, v204 op_sel_hi:[0,0,0] cbsz:2 blgp:2
	v_mfma_scale_f32_16x16x128_f8f6f4 v[70:73], v[180:185], v[214:219], v[70:73], v204, v204 op_sel_hi:[0,0,0] cbsz:2 blgp:2
	v_mfma_scale_f32_16x16x128_f8f6f4 v[66:69], v[250:255], v[214:219], v[66:69], v204, v204 op_sel_hi:[0,0,0] cbsz:2 blgp:2
	v_mfma_scale_f32_16x16x128_f8f6f4 v[62:65], v[180:185], v[220:225], v[62:65], v204, v204 op_sel_hi:[0,0,0] cbsz:2 blgp:2
	v_mfma_scale_f32_16x16x128_f8f6f4 v[58:61], v[250:255], v[220:225], v[58:61], v204, v204 op_sel_hi:[0,0,0] cbsz:2 blgp:2
	v_mfma_scale_f32_16x16x128_f8f6f4 v[54:57], v[180:185], v[226:231], v[54:57], v204, v204 op_sel_hi:[0,0,0] cbsz:2 blgp:2
	v_mfma_scale_f32_16x16x128_f8f6f4 v[50:53], v[250:255], v[226:231], v[50:53], v204, v204 op_sel_hi:[0,0,0] cbsz:2 blgp:2
	s_waitcnt vmcnt(6)
	s_waitcnt lgkmcnt(0)
	s_barrier
	s_add_i32 s73, s73, 2
	s_add_u32 s2, s2, 0x6000
	s_addc_u32 s3, s3, 0
	s_add_u32 s33, s33, 0x6000
	s_addc_u32 s72, s72, 0
	s_cmp_gt_u32 s73, 29
	s_cbranch_scc0 .Lsp1_top_L1
	s_branch .LBB0_992

.LBB0_1106:
	v_cvt_pk_bf16_f32 v4, v4, v5
	v_cvt_pk_bf16_f32 v5, v8, v9
	v_cvt_pk_bf16_f32 v6, v6, v7
	v_cvt_pk_bf16_f32 v7, v10, v11
	s_and_b64 vcc, exec, s[12:13]
	global_store_dwordx4 v[2:3], v[4:7], off offset:256
	s_cbranch_vccnz .LBB0_967
	s_and_b64 vcc, exec, s[8:9]
	s_cbranch_vccnz .LBB0_966
	s_nop 0
	s_branch .LBB0_966

	.amdhsa_kernel _Z6mk_fwd4Args
		.amdhsa_group_segment_fixed_size 0
		.amdhsa_private_segment_fixed_size 0
		.amdhsa_kernarg_size 400
		.amdhsa_user_sgpr_count 2
		.amdhsa_user_sgpr_dispatch_ptr 0
		.amdhsa_user_sgpr_queue_ptr 0
		.amdhsa_user_sgpr_kernarg_segment_ptr 1
		.amdhsa_user_sgpr_dispatch_id 0
		.amdhsa_user_sgpr_kernarg_preload_length 0
		.amdhsa_user_sgpr_kernarg_preload_offset 0
		.amdhsa_user_sgpr_private_segment_size 0
		.amdhsa_uses_dynamic_stack 0
		.amdhsa_enable_private_segment 0
		.amdhsa_system_sgpr_workgroup_id_x 1
		.amdhsa_system_sgpr_workgroup_id_y 0
		.amdhsa_system_sgpr_workgroup_id_z 0
		.amdhsa_system_sgpr_workgroup_info 0
		.amdhsa_system_vgpr_workitem_id 0
		.amdhsa_next_free_vgpr 256
		.amdhsa_next_free_sgpr 98
		.amdhsa_accum_offset 256
		.amdhsa_reserve_vcc 1
		.amdhsa_float_round_mode_32 0
		.amdhsa_float_round_mode_16_64 0
		.amdhsa_float_denorm_mode_32 3
		.amdhsa_float_denorm_mode_16_64 3
		.amdhsa_dx10_clamp 1
		.amdhsa_ieee_mode 1
		.amdhsa_fp16_overflow 0
		.amdhsa_tg_split 0
		.amdhsa_exception_fp_ieee_invalid_op 0
		.amdhsa_exception_fp_denorm_src 0
		.amdhsa_exception_fp_ieee_div_zero 0
		.amdhsa_exception_fp_ieee_overflow 0
		.amdhsa_exception_fp_ieee_underflow 0
		.amdhsa_exception_fp_ieee_inexact 0
		.amdhsa_exception_int_div_zero 0
	.end_amdhsa_kernel

amdhsa.kernels:
  - .agpr_count:     0
    .args:
      - .offset:         0
        .size:           144
        .value_kind:     by_value
      - .offset:         144
        .size:           4
        .value_kind:     hidden_block_count_x
      - .offset:         148
        .size:           4
        .value_kind:     hidden_block_count_y
      - .offset:         152
        .size:           4
        .value_kind:     hidden_block_count_z
      - .offset:         156
        .size:           2
        .value_kind:     hidden_group_size_x
      - .offset:         158
        .size:           2
        .value_kind:     hidden_group_size_y
      - .offset:         160
        .size:           2
        .value_kind:     hidden_group_size_z
      - .offset:         162
        .size:           2
        .value_kind:     hidden_remainder_x
      - .offset:         164
        .size:           2
        .value_kind:     hidden_remainder_y
      - .offset:         166
        .size:           2
        .value_kind:     hidden_remainder_z
      - .offset:         184
        .size:           8
        .value_kind:     hidden_global_offset_x
      - .offset:         192
        .size:           8
        .value_kind:     hidden_global_offset_y
      - .offset:         200
        .size:           8
        .value_kind:     hidden_global_offset_z
      - .offset:         208
        .size:           2
        .value_kind:     hidden_grid_dims
      - .offset:         264
        .size:           4
        .value_kind:     hidden_dynamic_lds_size
    .group_segment_fixed_size: 0
    .kernarg_segment_align: 8
    .kernarg_segment_size: 400
    .language:       OpenCL C
    .language_version:
      - 2
      - 0
    .max_flat_workgroup_size: 512
    .name:           _Z6mk_fwd4Args
    .private_segment_fixed_size: 0
    .sgpr_count:     104
    .sgpr_spill_count: 267
    .symbol:         _Z6mk_fwd4Args.kd
    .uniform_work_group_size: 1
    .uses_dynamic_stack: false
    .vgpr_count:     256
    .vgpr_spill_count: 0
    .wavefront_size: 64
